# v5b + P3 workgroups staggered: odd groups of 8 start 16 us late so tile epilogues interleave
# baseline (speedup 1.0000x reference)
; #define PG8_STAGE(bufoff, gbase, voff) do { _Pragma("unroll") for (int _i = 0; _i < 2; ++_i) \
;         __builtin_amdgcn_global_load_lds((const unsigned*)((const char*)(gbase) + (voff)[_i]), (LAS unsigned*)(lds + (bufoff) + ldsw + _i * 8192), 16, 0, 0); } while (0)
; #define PG8_WAIT_V(n) asm volatile("s_waitcnt vmcnt(" #n ")" ::: "memory")
; #define PG8_BAR __builtin_amdgcn_s_barrier()
; template <class Epi, class Ptrs>
; __device__ __forceinline__ void gemm_phase(LAS unsigned char* lds, const int K, const StaticOrder& S, const Ptrs& P, const Epi& E) {
;     const int tid = threadIdx.x, wid = __builtin_amdgcn_readfirstlane(tid >> 6), lane = tid & 63, wr = wid >> 2, wc = wid & 3, fr = lane & 15, fq = lane >> 4;
;     const int nt = K / BK;
;     unsigned voffA[2], voffB[2];
; #pragma unroll
;     for (int i = 0; i < 2; ++i) { int R, C; stage_rc(tid * 16 + i * 8192, R, C); const int Rb = (R & ~31) + perm32(R & 31);
;         voffA[i] = (unsigned)(R * K + C) * 2u; voffB[i] = (unsigned)(Rb * K + C) * 2u; }
;     const size_t kstep = (size_t)(BK * 2);
;     const size_t hstep = (size_t)HALF * K * 2;
;     const unsigned ldsw = (unsigned)wid * 1024u;
;     const int aoff = lds_byte(wr * 64 + fr, fq * 8), boff = lds_byte(wc * 32 + fr, fq * 8);
;     ...
;     Unit cur, nxt; int ui = 0;
;     if (!S.next(0, cur)) return;
;     f32x4 acc[2][2][4][2];
; #pragma unroll
;     for (int a = 0; a < 2; ++a)
; #pragma unroll
;         for (int b = 0; b < 2; ++b)
; #pragma unroll
;             for (int m = 0; m < 4; ++m)
; #pragma unroll
;                 for (int n = 0; n < 2; ++n) acc[a][b][m][n] = (f32x4){0.f, 0.f, 0.f, 0.f};
;     bf16x8 At[4][2], B0[2][2], B1[2][2];
;     const char* cA; const char* cB; P.get(cur, cA, cB);
;     PG8_STAGE(PG8_SB(0, 0), cB, voffB); PG8_STAGE(PG8_SA(0, 0), cA, voffA); PG8_STAGE(PG8_SB(0, 1), cB + hstep, voffB); PG8_STAGE(PG8_SA(0, 1), cA + hstep, voffA);
;     if (wr == 1) PG8_BAR;
;     PG8_WAIT_V(4); PG8_BAR;
; __global__ void __launch_bounds__(512, 2) fwd_megakernel(Args a) {
;     ...
;     if (IN(3)) for (int rep = (PROBE_DUP == 3 ? 0 : 1); rep < 2; ++rep) {
;         pg8::StaticOrder S; S.init(MTOK, DM, G, bx);
;         pg8::PlainPtrs P{(const bf16_t*)(a.ws + WS_U), (const bf16_t*)(a.ws + WS_WOT), DM};
;         EpiWo E{a.in[I_XP], a.in[I_XS], (bf16_t*)(a.ws + WS_Q), (float*)(a.ws + WS_PART)};
;         pg8::gemm_phase(lds, DM, S, P, E);
.LBB0_343:
	s_andn2_b64 vcc, exec, s[0:1]
	s_cbranch_vccnz .LBB0_373
	s_and_b32 s88, s2, 8
	s_cmp_eq_u32 s88, 0
	s_cbranch_scc1 .Ldesync_p3_skip
	s_memrealtime s[90:91]
	s_waitcnt lgkmcnt(0)
.Ldesync_p3_wait:
	s_sleep 8
	s_memrealtime s[92:93]
	s_waitcnt lgkmcnt(0)
	s_sub_u32 s89, s92, s90
	s_cmp_lt_u32 s89, 1600
	s_cbranch_scc1 .Ldesync_p3_wait
.Ldesync_p3_skip:
	v_lshrrev_b32_e32 v2, 1, v208
	s_nop 0
	s_nop 0
	s_nop 0
	s_nop 0
	s_nop 0
	s_nop 0
	s_nop 0
	s_nop 0
	s_nop 0
	s_nop 0
	s_nop 0
	s_nop 0
	s_nop 0
	s_nop 0
	s_nop 0
	s_nop 0
	s_nop 0
	s_nop 0
	s_nop 0
	s_nop 0
	s_nop 0
	s_nop 0
	s_nop 0
	s_nop 0
	s_nop 0
	s_nop 0
	s_nop 0
	s_nop 0
	s_nop 0
	s_nop 0
	s_nop 0
	s_nop 0
	s_nop 0
	s_nop 0
	s_nop 0
	s_nop 0
	s_nop 0
	s_nop 0
	s_nop 0
	s_nop 0
	s_nop 0
	s_nop 0
	s_nop 0
	s_nop 0
	s_nop 0
	s_nop 0
	s_nop 0
	s_nop 0
	s_nop 0
	s_nop 0
	v_lshrrev_b32_e32 v3, 5, v208
	v_and_b32_e32 v2, 24, v2
	v_and_b32_e32 v3, 4, v3
	v_bfe_u32 v4, v208, 2, 2
	s_add_u32 s47, s28, 0xe000000
	v_lshlrev_b32_e32 v0, 4, v208
	v_and_b32_e32 v1, 32, v208
	v_bfe_u32 v10, v208, 2, 4
	v_or3_b32 v2, v3, v4, v2
	v_lshrrev_b32_e32 v3, 3, v208
	s_movk_i32 s0, 0x70
	s_addc_u32 s48, s29, 0
	v_bitop3_b32 v8, v0, v1, 48 bitop3:0x6c
	v_and_b32_e32 v9, 64, v208
	v_and_or_b32 v4, v3, s0, v10
	s_movk_i32 s0, 0x60
	v_add_u32_e32 v11, 0x2000, v0
	s_add_u32 s49, s28, 0xc00000
	v_or_b32_e32 v1, v8, v9
	v_and_or_b32 v3, v3, s0, v2
	v_lshrrev_b32_e32 v0, 7, v11
	s_movk_i32 s0, 0xf0
	s_addc_u32 s50, s29, 0
	v_lshl_or_b32 v178, v3, 11, v1
	v_and_or_b32 v3, v0, s0, v10
	s_movk_i32 s0, 0xe0
	s_lshr_b32 s1, s46, 6
	s_ashr_i32 s41, s40, 31
	s_ashr_i32 s13, s12, 31
	v_and_or_b32 v0, v0, s0, v2
	s_lshr_b32 s0, s46, 8
	s_lshl_b32 s51, s1, 10
	s_lshl_b64 s[4:5], s[40:41], 19
	s_lshl_b64 s[6:7], s[12:13], 19
	s_add_u32 s42, s49, s6
	s_addc_u32 s43, s50, s7
	s_add_i32 s54, s51, 0
	s_add_i32 m0, s54, 0x10000
	v_lshl_or_b32 v182, v0, 11, v1
	global_load_lds_dwordx4 v178, s[42:43]
	s_add_i32 m0, s54, 0x12000
	s_add_u32 s44, s47, s4
	v_lshl_or_b32 v176, v4, 11, v1
	global_load_lds_dwordx4 v182, s[42:43]
	s_addc_u32 s45, s48, s5
	s_mov_b32 m0, s54
	s_add_i32 s55, s54, 0x2000
	v_lshl_or_b32 v180, v3, 11, v1
	global_load_lds_dwordx4 v176, s[44:45]
	s_mov_b32 m0, s55
	s_add_u32 s4, s42, 0x40000
	global_load_lds_dwordx4 v180, s[44:45]
	s_addc_u32 s5, s43, 0
	s_add_i32 m0, s54, 0x14000
	v_mov_b32_e32 v179, 0
	global_load_lds_dwordx4 v178, s[4:5]
	s_add_i32 m0, s54, 0x16000
	v_mov_b32_e32 v183, v179
	global_load_lds_dwordx4 v182, s[4:5]
	s_add_u32 s4, s44, 0x40000
	s_addc_u32 s5, s45, 0
	s_add_i32 s56, s54, 0x4000
	s_mov_b32 m0, s56
	s_add_i32 s57, s54, 0x6000
	global_load_lds_dwordx4 v176, s[4:5]
	s_mov_b32 m0, s57
	v_mov_b32_e32 v177, v179
	global_load_lds_dwordx4 v180, s[4:5]
	v_mov_b32_e32 v181, v179
	s_mov_b32 s13, 0
	v_lshl_add_u64 v[6:7], s[42:43], 0, v[178:179]
	v_lshl_add_u64 v[4:5], s[42:43], 0, v[182:183]
	v_lshl_add_u64 v[2:3], s[44:45], 0, v[176:177]
	s_cmp_lg_u32 s0, 1
	v_lshl_add_u64 v[0:1], s[44:45], 0, v[180:181]
	s_cbranch_scc1 .LBB0_346
	s_barrier

; #define LAS __attribute__((address_space(3)))
; __global__ void __launch_bounds__(512, 2) fwd_megakernel(Args a) {
;     extern __shared__ __attribute__((aligned(16))) unsigned char shm[];
;     LAS unsigned char* lds = (LAS unsigned char*)shm;
;     const int tid = threadIdx.x, lane = tid & 63, wave = __builtin_amdgcn_readfirstlane(tid >> 6);
;     const int G = gridDim.x, bx = blockIdx.x;
	.amdhsa_kernel _Z14fwd_megakernel4Args
		.amdhsa_group_segment_fixed_size 0
		.amdhsa_private_segment_fixed_size 0
		.amdhsa_kernarg_size 400
		.amdhsa_user_sgpr_count 2
		.amdhsa_user_sgpr_dispatch_ptr 0
		.amdhsa_user_sgpr_queue_ptr 0
		.amdhsa_user_sgpr_kernarg_segment_ptr 1
		.amdhsa_user_sgpr_dispatch_id 0
		.amdhsa_user_sgpr_kernarg_preload_length 0
		.amdhsa_user_sgpr_kernarg_preload_offset 0
		.amdhsa_user_sgpr_private_segment_size 0
		.amdhsa_uses_dynamic_stack 0
		.amdhsa_enable_private_segment 0
		.amdhsa_system_sgpr_workgroup_id_x 1
		.amdhsa_system_sgpr_workgroup_id_y 0
		.amdhsa_system_sgpr_workgroup_id_z 0
		.amdhsa_system_sgpr_workgroup_info 0
		.amdhsa_system_vgpr_workitem_id 2
		.amdhsa_next_free_vgpr 255
		.amdhsa_next_free_sgpr 102
		.amdhsa_accum_offset 256
		.amdhsa_reserve_vcc 1
		.amdhsa_float_round_mode_32 0
		.amdhsa_float_round_mode_16_64 0
		.amdhsa_float_denorm_mode_32 3
		.amdhsa_float_denorm_mode_16_64 3
		.amdhsa_dx10_clamp 1
		.amdhsa_ieee_mode 1
		.amdhsa_fp16_overflow 0
		.amdhsa_tg_split 0
		.amdhsa_exception_fp_ieee_invalid_op 0
		.amdhsa_exception_fp_denorm_src 0
		.amdhsa_exception_fp_ieee_div_zero 0
		.amdhsa_exception_fp_ieee_overflow 0
		.amdhsa_exception_fp_ieee_underflow 0
		.amdhsa_exception_fp_ieee_inexact 0
		.amdhsa_exception_int_div_zero 0
	.end_amdhsa_kernel

; __global__ void __launch_bounds__(512, 2) fwd_megakernel(Args a) {
.Lfunc_end0:
	.size	_Z14fwd_megakernel4Args, .Lfunc_end0-_Z14fwd_megakernel4Args
	.set _Z14fwd_megakernel4Args.num_vgpr, 255
	.set _Z14fwd_megakernel4Args.num_agpr, 0
	.set _Z14fwd_megakernel4Args.numbered_sgpr, 102
	.set _Z14fwd_megakernel4Args.num_named_barrier, 0
	.set _Z14fwd_megakernel4Args.private_seg_size, 0
	.set _Z14fwd_megakernel4Args.uses_vcc, 1
	.set _Z14fwd_megakernel4Args.uses_flat_scratch, 0
	.set _Z14fwd_megakernel4Args.has_dyn_sized_stack, 0
	.set _Z14fwd_megakernel4Args.has_recursion, 0
	.set _Z14fwd_megakernel4Args.has_indirect_call, 0

; __global__ void __launch_bounds__(512, 2) fwd_megakernel(Args a) {
amdhsa.kernels:
  - .agpr_count:     0
    .args:
      - .offset:         0
        .size:           144
        .value_kind:     by_value
      - .offset:         144
        .size:           4
        .value_kind:     hidden_block_count_x
      - .offset:         148
        .size:           4
        .value_kind:     hidden_block_count_y
      - .offset:         152
        .size:           4
        .value_kind:     hidden_block_count_z
      - .offset:         156
        .size:           2
        .value_kind:     hidden_group_size_x
      - .offset:         158
        .size:           2
        .value_kind:     hidden_group_size_y
      - .offset:         160
        .size:           2
        .value_kind:     hidden_group_size_z
      - .offset:         162
        .size:           2
        .value_kind:     hidden_remainder_x
      - .offset:         164
        .size:           2
        .value_kind:     hidden_remainder_y
      - .offset:         166
        .size:           2
        .value_kind:     hidden_remainder_z
      - .offset:         184
        .size:           8
        .value_kind:     hidden_global_offset_x
      - .offset:         192
        .size:           8
        .value_kind:     hidden_global_offset_y
      - .offset:         200
        .size:           8
        .value_kind:     hidden_global_offset_z
      - .offset:         208
        .size:           2
        .value_kind:     hidden_grid_dims
      - .offset:         232
        .size:           8
        .value_kind:     hidden_multigrid_sync_arg
      - .offset:         264
        .size:           4
        .value_kind:     hidden_dynamic_lds_size
    .group_segment_fixed_size: 0
    .kernarg_segment_align: 8
    .kernarg_segment_size: 400
    .language:       OpenCL C
    .language_version:
      - 2
      - 0
    .max_flat_workgroup_size: 512
    .name:           _Z14fwd_megakernel4Args
    .private_segment_fixed_size: 0
    .sgpr_count:     108
    .sgpr_spill_count: 4
    .symbol:         _Z14fwd_megakernel4Args.kd
    .uniform_work_group_size: 1
    .uses_dynamic_stack: false
    .vgpr_count:     255
    .vgpr_spill_count: 0
    .wavefront_size: 64
